# v34 + non-temporal loads for the read-once f32 inputs in the prologue (conversions and weight transposes)
# baseline (speedup 1.0000x reference)
; #define LAS __attribute__((address_space(3)))
; #define GASP __attribute__((address_space(1)))
; __device__ __forceinline__ void transpose_item(const float* W, int K, int N, bf16_t* WT, int item, int gu, LAS float* tile,
;                                                const float* gam = nullptr, const float* bet = nullptr, float* c1p = nullptr, float* c2p = nullptr) {
;     const int tid = threadIdx.x, nblk = N / 64, kb = item / nblk, nb = item % nblk, k0 = kb * 64, n0 = nb * 64;
;     { const int r = tid >> 3, c8 = (tid & 7) * 8; const float* src = W + (size_t)(k0 + r) * N + n0 + c8;
;       const f32x4 a = *(const GASP f32x4*)src, b = *(const GASP f32x4*)(src + 4);
;       LAS float* t = tile + r * 65 + c8; t[0] = a[0]; t[1] = a[1]; t[2] = a[2]; t[3] = a[3]; t[4] = b[0]; t[5] = b[1]; t[6] = b[2]; t[7] = b[3]; }
;     __syncthreads();
;     { const int n = tid >> 3, k8 = (tid & 7) * 8; const LAS float* t = tile + k8 * 65 + n;
;       float w[8];
; #pragma unroll
;       for (int i = 0; i < 8; ++i) w[i] = t[i * 65];
;       int nn = n0 + n; if (gu) nn = (nn < FF) ? ((nn >> 7) * 256 + (nn & 127)) : (((nn - FF) >> 7) * 256 + 128 + ((nn - FF) & 127));
;       float s2 = 0.f;
;       if (gam) {
; #pragma unroll
;           for (int i = 0; i < 8; ++i) { s2 += bet[k0 + k8 + i] * w[i]; w[i] *= gam[k0 + k8 + i]; }
;       }
;       u32x4 o; o.x = pk2(w[0], w[1]); o.y = pk2(w[2], w[3]); o.z = pk2(w[4], w[5]); o.w = pk2(w[6], w[7]);
;       *(GASP u32x4*)(WT + (size_t)nn * K + k0 + k8) = o;
;       if (gam) {
;           float s1 = ((__uint_as_float(o.x << 16) + __uint_as_float(o.x & 0xffff0000u)) + (__uint_as_float(o.y << 16) + __uint_as_float(o.y & 0xffff0000u)))
;                    + ((__uint_as_float(o.z << 16) + __uint_as_float(o.z & 0xffff0000u)) + (__uint_as_float(o.w << 16) + __uint_as_float(o.w & 0xffff0000u)));
;           s1 += __shfl_xor(s1, 1); s1 += __shfl_xor(s1, 2); s1 += __shfl_xor(s1, 4);
;           s2 += __shfl_xor(s2, 1); s2 += __shfl_xor(s2, 2); s2 += __shfl_xor(s2, 4);
;           if ((tid & 7) == 0) { c1p[(size_t)kb * NC12 + nn] = s1; c2p[(size_t)kb * NC12 + nn] = s2; }
;       } }
;     __syncthreads();
; }
; __device__ __forceinline__ void phase_prep(const Params& p, LAS unsigned char* lds) {
;     ...
;         if (r < I_SQ) { transpose_item(p.in[25], D, D, (bf16_t*)(ws + O_WKV), r, 0, tile); continue; } r -= I_SQ;
.LBB0_23:
	s_cmpk_gt_i32 s90, 0x57f
	s_mov_b64 s[8:9], -1
	s_cbranch_scc0 .LBB0_82
	s_cmpk_gt_u32 s90, 0xaff
	s_cbranch_scc0 .LBB0_68
	s_cmpk_gt_u32 s90, 0xdbf
	s_cbranch_scc0 .LBB0_65
	s_cmpk_gt_u32 s90, 0x107f
	s_cbranch_scc0 .LBB0_62
	s_cmpk_gt_u32 s90, 0x12ff
	s_cbranch_scc0 .LBB0_52
	s_cmpk_gt_u32 s90, 0x13ff
	s_cbranch_scc0 .LBB0_49
	s_and_b32 s91, s0, 0x3c0
	s_cmpk_gt_u32 s90, 0x14ff
	s_cbranch_scc0 .LBB0_39
	s_and_b32 s10, s5, 0x3c0
	s_cmpk_gt_u32 s90, 0x15ff
	v_add_lshl_u32 v0, s10, v5, 10
	s_cbranch_scc0 .LBB0_36
	s_cmpk_gt_u32 s90, 0x16ff
	s_cbranch_scc0 .LBB0_33
	v_lshlrev_b32_e32 v6, 2, v0
	v_lshl_add_u64 v[2:3], s[48:49], 0, v[6:7]
	s_lshl_b32 s96, s91, 2
	v_lshl_add_u64 v[2:3], v[2:3], 0, s[96:97]
	v_mov_b32_e32 v9, v7
	v_lshl_add_u64 v[2:3], v[2:3], 0, v[8:9]
	global_load_dwordx4 v[12:15], v[2:3], off nt
	global_load_dwordx4 v[24:27], v[2:3], off offset:16 nt
	v_readlane_b32 s8, v252, 8
	v_add_lshl_u32 v6, s91, v5, 11
	v_readlane_b32 s9, v252, 9
	s_lshl_b32 s96, s10, 1
	v_mov_b32_e32 v11, v7
	v_lshl_add_u64 v[2:3], s[8:9], 0, v[6:7]
	v_lshl_add_u64 v[2:3], v[2:3], 0, s[96:97]
	v_lshl_add_u64 v[2:3], v[2:3], 0, v[10:11]
	s_mov_b64 s[8:9], 0
	s_waitcnt vmcnt(0)
	ds_write2_b32 v18, v12, v13 offset1:1
	ds_write2_b32 v18, v14, v15 offset0:2 offset1:3
	ds_write2_b32 v18, v24, v25 offset0:4 offset1:5
	ds_write2_b32 v18, v26, v27 offset0:6 offset1:7
	s_waitcnt lgkmcnt(0)
	s_barrier
	ds_read2_b32 v[12:13], v19 offset1:65
	ds_read2_b32 v[14:15], v19 offset0:130 offset1:195
	ds_read2_b32 v[16:17], v22 offset0:4 offset1:69
	ds_read2_b32 v[24:25], v22 offset0:134 offset1:199
	s_waitcnt lgkmcnt(3)
	v_cvt_pk_bf16_f32 v12, v12, v13
	s_waitcnt lgkmcnt(2)
	v_cvt_pk_bf16_f32 v13, v14, v15
	s_waitcnt lgkmcnt(1)
	v_cvt_pk_bf16_f32 v14, v16, v17
	s_waitcnt lgkmcnt(0)
	v_cvt_pk_bf16_f32 v15, v24, v25
	global_store_dwordx4 v[2:3], v[12:15], off
	s_barrier
.LBB0_33:
	s_andn2_b64 vcc, exec, s[8:9]
	s_cbranch_vccnz .LBB0_35
	v_lshlrev_b32_e32 v6, 2, v0
	v_lshl_add_u64 v[2:3], s[46:47], 0, v[6:7]
	s_lshl_b32 s96, s91, 2
	v_lshl_add_u64 v[2:3], v[2:3], 0, s[96:97]
	v_mov_b32_e32 v9, v7
	v_lshl_add_u64 v[2:3], v[2:3], 0, v[8:9]
	global_load_dwordx4 v[12:15], v[2:3], off nt
	global_load_dwordx4 v[24:27], v[2:3], off offset:16 nt
	v_readlane_b32 s8, v252, 10
	v_add_lshl_u32 v6, s91, v5, 11
	v_readlane_b32 s9, v252, 11
	s_lshl_b32 s96, s10, 1
	v_mov_b32_e32 v11, v7
	v_lshl_add_u64 v[2:3], s[8:9], 0, v[6:7]
	v_lshl_add_u64 v[2:3], v[2:3], 0, s[96:97]
	v_lshl_add_u64 v[2:3], v[2:3], 0, v[10:11]
	s_waitcnt vmcnt(0)
	ds_write2_b32 v18, v12, v13 offset1:1
	ds_write2_b32 v18, v14, v15 offset0:2 offset1:3
	ds_write2_b32 v18, v24, v25 offset0:4 offset1:5
	ds_write2_b32 v18, v26, v27 offset0:6 offset1:7
	s_waitcnt lgkmcnt(0)
	s_barrier
	ds_read2_b32 v[12:13], v19 offset1:65
	ds_read2_b32 v[14:15], v19 offset0:130 offset1:195
	ds_read2_b32 v[16:17], v22 offset0:4 offset1:69
	ds_read2_b32 v[24:25], v22 offset0:134 offset1:199
	s_waitcnt lgkmcnt(3)
	v_cvt_pk_bf16_f32 v12, v12, v13
	s_waitcnt lgkmcnt(2)
	v_cvt_pk_bf16_f32 v13, v14, v15
	s_waitcnt lgkmcnt(1)
	v_cvt_pk_bf16_f32 v14, v16, v17
	s_waitcnt lgkmcnt(0)
	v_cvt_pk_bf16_f32 v15, v24, v25
	global_store_dwordx4 v[2:3], v[12:15], off
	s_barrier

; #define LAS __attribute__((address_space(3)))
; #define GASP __attribute__((address_space(1)))
; __device__ __forceinline__ void transpose_item(const float* W, int K, int N, bf16_t* WT, int item, int gu, LAS float* tile,
;                                                const float* gam = nullptr, const float* bet = nullptr, float* c1p = nullptr, float* c2p = nullptr) {
;     const int tid = threadIdx.x, nblk = N / 64, kb = item / nblk, nb = item % nblk, k0 = kb * 64, n0 = nb * 64;
;     { const int r = tid >> 3, c8 = (tid & 7) * 8; const float* src = W + (size_t)(k0 + r) * N + n0 + c8;
;       const f32x4 a = *(const GASP f32x4*)src, b = *(const GASP f32x4*)(src + 4);
;       LAS float* t = tile + r * 65 + c8; t[0] = a[0]; t[1] = a[1]; t[2] = a[2]; t[3] = a[3]; t[4] = b[0]; t[5] = b[1]; t[6] = b[2]; t[7] = b[3]; }
;     __syncthreads();
;     { const int n = tid >> 3, k8 = (tid & 7) * 8; const LAS float* t = tile + k8 * 65 + n;
;       float w[8];
; #pragma unroll
;       for (int i = 0; i < 8; ++i) w[i] = t[i * 65];
;       int nn = n0 + n; if (gu) nn = (nn < FF) ? ((nn >> 7) * 256 + (nn & 127)) : (((nn - FF) >> 7) * 256 + 128 + ((nn - FF) & 127));
;       float s2 = 0.f;
;       if (gam) {
; #pragma unroll
;           for (int i = 0; i < 8; ++i) { s2 += bet[k0 + k8 + i] * w[i]; w[i] *= gam[k0 + k8 + i]; }
;       }
;       u32x4 o; o.x = pk2(w[0], w[1]); o.y = pk2(w[2], w[3]); o.z = pk2(w[4], w[5]); o.w = pk2(w[6], w[7]);
;       *(GASP u32x4*)(WT + (size_t)nn * K + k0 + k8) = o;
;       if (gam) {
;           float s1 = ((__uint_as_float(o.x << 16) + __uint_as_float(o.x & 0xffff0000u)) + (__uint_as_float(o.y << 16) + __uint_as_float(o.y & 0xffff0000u)))
;                    + ((__uint_as_float(o.z << 16) + __uint_as_float(o.z & 0xffff0000u)) + (__uint_as_float(o.w << 16) + __uint_as_float(o.w & 0xffff0000u)));
;           s1 += __shfl_xor(s1, 1); s1 += __shfl_xor(s1, 2); s1 += __shfl_xor(s1, 4);
;           s2 += __shfl_xor(s2, 1); s2 += __shfl_xor(s2, 2); s2 += __shfl_xor(s2, 4);
;           if ((tid & 7) == 0) { c1p[(size_t)kb * NC12 + nn] = s1; c2p[(size_t)kb * NC12 + nn] = s2; }
;       } }
;     __syncthreads();
; }
; __device__ __forceinline__ void phase_prep(const Params& p, LAS unsigned char* lds) {
;     ...
;         if (r < I_SQ) { transpose_item(p.in[25], D, D, (bf16_t*)(ws + O_WKV), r, 0, tile); continue; } r -= I_SQ;
.LBB0_36:
	s_andn2_b64 vcc, exec, s[8:9]
	s_cbranch_vccnz .LBB0_38
	v_lshlrev_b32_e32 v6, 2, v0
	v_lshl_add_u64 v[0:1], s[44:45], 0, v[6:7]
	s_lshl_b32 s96, s91, 2
	v_lshl_add_u64 v[0:1], v[0:1], 0, s[96:97]
	v_mov_b32_e32 v9, v7
	v_lshl_add_u64 v[12:13], v[0:1], 0, v[8:9]
	global_load_dwordx4 v[0:3], v[12:13], off nt
	s_nop 0
	global_load_dwordx4 v[12:15], v[12:13], off offset:16 nt
	v_add_lshl_u32 v6, s91, v5, 11
	v_lshl_add_u64 v[16:17], s[62:63], 0, v[6:7]
	s_lshl_b32 s96, s10, 1
	v_mov_b32_e32 v11, v7
	v_lshl_add_u64 v[16:17], v[16:17], 0, s[96:97]
	v_lshl_add_u64 v[16:17], v[16:17], 0, v[10:11]
	s_waitcnt vmcnt(0)
	ds_write2_b32 v18, v0, v1 offset1:1
	ds_write2_b32 v18, v2, v3 offset0:2 offset1:3
	ds_write2_b32 v18, v12, v13 offset0:4 offset1:5
	ds_write2_b32 v18, v14, v15 offset0:6 offset1:7
	s_waitcnt lgkmcnt(0)
	s_barrier
	ds_read2_b32 v[0:1], v19 offset1:65
	ds_read2_b32 v[2:3], v19 offset0:130 offset1:195
	ds_read2_b32 v[12:13], v22 offset0:4 offset1:69
	ds_read2_b32 v[14:15], v22 offset0:134 offset1:199
	s_waitcnt lgkmcnt(3)
	v_cvt_pk_bf16_f32 v0, v0, v1
	s_waitcnt lgkmcnt(2)
	v_cvt_pk_bf16_f32 v1, v2, v3
	s_waitcnt lgkmcnt(1)
	v_cvt_pk_bf16_f32 v2, v12, v13
	s_waitcnt lgkmcnt(0)
	v_cvt_pk_bf16_f32 v3, v14, v15
	global_store_dwordx4 v[16:17], v[0:3], off
	s_barrier

; #define LAS __attribute__((address_space(3)))
; #define GASP __attribute__((address_space(1)))
; __device__ __forceinline__ void transpose_item(const float* W, int K, int N, bf16_t* WT, int item, int gu, LAS float* tile,
;                                                const float* gam = nullptr, const float* bet = nullptr, float* c1p = nullptr, float* c2p = nullptr) {
;     const int tid = threadIdx.x, nblk = N / 64, kb = item / nblk, nb = item % nblk, k0 = kb * 64, n0 = nb * 64;
;     { const int r = tid >> 3, c8 = (tid & 7) * 8; const float* src = W + (size_t)(k0 + r) * N + n0 + c8;
;       const f32x4 a = *(const GASP f32x4*)src, b = *(const GASP f32x4*)(src + 4);
;       LAS float* t = tile + r * 65 + c8; t[0] = a[0]; t[1] = a[1]; t[2] = a[2]; t[3] = a[3]; t[4] = b[0]; t[5] = b[1]; t[6] = b[2]; t[7] = b[3]; }
;     __syncthreads();
;     { const int n = tid >> 3, k8 = (tid & 7) * 8; const LAS float* t = tile + k8 * 65 + n;
;       float w[8];
; #pragma unroll
;       for (int i = 0; i < 8; ++i) w[i] = t[i * 65];
;       int nn = n0 + n; if (gu) nn = (nn < FF) ? ((nn >> 7) * 256 + (nn & 127)) : (((nn - FF) >> 7) * 256 + 128 + ((nn - FF) & 127));
;       float s2 = 0.f;
;       if (gam) {
; #pragma unroll
;           for (int i = 0; i < 8; ++i) { s2 += bet[k0 + k8 + i] * w[i]; w[i] *= gam[k0 + k8 + i]; }
; __device__ __forceinline__ void phase_prep(const Params& p, LAS unsigned char* lds) {
;     ...
;         if (r < I_SQ) { transpose_item(p.in[24], D, D, (bf16_t*)(ws + O_WQ), r, 0, tile, p.in[22], p.in[23], (float*)(ws + O_C1P) + C_Q, (float*)(ws + O_C2P) + C_Q); continue; } r -= I_SQ;
.LBB0_39:
	s_andn2_b64 vcc, exec, s[8:9]
	s_cbranch_vccnz .LBB0_48
	s_bfe_u32 s10, s90, 0x40004
	s_lshl_b32 s11, s10, 6
	v_add_lshl_u32 v6, s11, v5, 12
	v_lshl_add_u64 v[0:1], s[42:43], 0, v[6:7]
	s_lshl_b32 s96, s91, 2
	v_lshl_add_u64 v[0:1], v[0:1], 0, s[96:97]
	v_mov_b32_e32 v9, v7
	v_lshl_add_u64 v[12:13], v[0:1], 0, v[8:9]
	global_load_dwordx4 v[0:3], v[12:13], off nt
	s_nop 0
	global_load_dwordx4 v[12:15], v[12:13], off offset:16 nt
	v_readlane_b32 s60, v252, 12
	v_readlane_b32 s61, v252, 13
	v_cmp_ne_u32_e64 s[8:9], 1, v20
	s_andn2_b64 vcc, exec, s[60:61]
	s_cbranch_vccnz .Lgm_a
	v_or_b32_e32 v40, s11, v4
	v_lshlrev_b32_e32 v40, 2, v40
	global_load_dwordx4 v[24:27], v40, s[40:41]
	global_load_dwordx4 v[28:31], v40, s[40:41] offset:16
	global_load_dwordx4 v[32:35], v40, s[38:39]
	global_load_dwordx4 v[36:39], v40, s[38:39] offset:16

; #define LAS __attribute__((address_space(3)))
; #define GASP __attribute__((address_space(1)))
; __device__ __forceinline__ void transpose_item(const float* W, int K, int N, bf16_t* WT, int item, int gu, LAS float* tile,
;                                                const float* gam = nullptr, const float* bet = nullptr, float* c1p = nullptr, float* c2p = nullptr) {
;     const int tid = threadIdx.x, nblk = N / 64, kb = item / nblk, nb = item % nblk, k0 = kb * 64, n0 = nb * 64;
;     { const int r = tid >> 3, c8 = (tid & 7) * 8; const float* src = W + (size_t)(k0 + r) * N + n0 + c8;
;       const f32x4 a = *(const GASP f32x4*)src, b = *(const GASP f32x4*)(src + 4);
;       LAS float* t = tile + r * 65 + c8; t[0] = a[0]; t[1] = a[1]; t[2] = a[2]; t[3] = a[3]; t[4] = b[0]; t[5] = b[1]; t[6] = b[2]; t[7] = b[3]; }
;     __syncthreads();
;     { const int n = tid >> 3, k8 = (tid & 7) * 8; const LAS float* t = tile + k8 * 65 + n;
;       float w[8];
; #pragma unroll
;       for (int i = 0; i < 8; ++i) w[i] = t[i * 65];
;       int nn = n0 + n; if (gu) nn = (nn < FF) ? ((nn >> 7) * 256 + (nn & 127)) : (((nn - FF) >> 7) * 256 + 128 + ((nn - FF) & 127));
;       float s2 = 0.f;
;       if (gam) {
; #pragma unroll
;           for (int i = 0; i < 8; ++i) { s2 += bet[k0 + k8 + i] * w[i]; w[i] *= gam[k0 + k8 + i]; }
;       }
;       u32x4 o; o.x = pk2(w[0], w[1]); o.y = pk2(w[2], w[3]); o.z = pk2(w[4], w[5]); o.w = pk2(w[6], w[7]);
;       *(GASP u32x4*)(WT + (size_t)nn * K + k0 + k8) = o;
;       if (gam) {
;           float s1 = ((__uint_as_float(o.x << 16) + __uint_as_float(o.x & 0xffff0000u)) + (__uint_as_float(o.y << 16) + __uint_as_float(o.y & 0xffff0000u)))
;                    + ((__uint_as_float(o.z << 16) + __uint_as_float(o.z & 0xffff0000u)) + (__uint_as_float(o.w << 16) + __uint_as_float(o.w & 0xffff0000u)));
;           s1 += __shfl_xor(s1, 1); s1 += __shfl_xor(s1, 2); s1 += __shfl_xor(s1, 4);
;           s2 += __shfl_xor(s2, 1); s2 += __shfl_xor(s2, 2); s2 += __shfl_xor(s2, 4);
;           if ((tid & 7) == 0) { c1p[(size_t)kb * NC12 + nn] = s1; c2p[(size_t)kb * NC12 + nn] = s2; }
;       } }
;     __syncthreads();
; }
; __device__ __forceinline__ void phase_prep(const Params& p, LAS unsigned char* lds) {
;     ...
;         if (r < I_SQ) { transpose_item(p.in[21], D, D, (bf16_t*)(ws + O_WOUT), r, 0, tile); continue; } r -= I_SQ;
.LBB0_49:
	s_andn2_b64 vcc, exec, s[8:9]
	s_cbranch_vccnz .LBB0_51
	s_and_b32 s8, s5, 0x3c0
	s_and_b32 s9, s0, 0x3c0
	v_add_lshl_u32 v6, s8, v5, 12
	v_lshl_add_u64 v[0:1], s[36:37], 0, v[6:7]
	s_lshl_b32 s96, s9, 2
	v_lshl_add_u64 v[0:1], v[0:1], 0, s[96:97]
	v_mov_b32_e32 v9, v7
	v_lshl_add_u64 v[12:13], v[0:1], 0, v[8:9]
	global_load_dwordx4 v[0:3], v[12:13], off nt
	s_nop 0
	global_load_dwordx4 v[12:15], v[12:13], off offset:16 nt
	v_add_lshl_u32 v6, s9, v5, 11
	v_lshl_add_u64 v[16:17], s[70:71], 0, v[6:7]
	s_lshl_b32 s96, s8, 1
	v_mov_b32_e32 v11, v7
	v_lshl_add_u64 v[16:17], v[16:17], 0, s[96:97]
	v_lshl_add_u64 v[16:17], v[16:17], 0, v[10:11]
	s_waitcnt vmcnt(0)
	ds_write2_b32 v18, v0, v1 offset1:1
	ds_write2_b32 v18, v2, v3 offset0:2 offset1:3
	ds_write2_b32 v18, v12, v13 offset0:4 offset1:5
	ds_write2_b32 v18, v14, v15 offset0:6 offset1:7
	s_waitcnt lgkmcnt(0)
	s_barrier
	ds_read2_b32 v[0:1], v19 offset1:65
	ds_read2_b32 v[2:3], v19 offset0:130 offset1:195
	ds_read2_b32 v[12:13], v22 offset0:4 offset1:69
	ds_read2_b32 v[14:15], v22 offset0:134 offset1:199
	s_waitcnt lgkmcnt(3)
	v_cvt_pk_bf16_f32 v0, v0, v1
	s_waitcnt lgkmcnt(2)
	v_cvt_pk_bf16_f32 v1, v2, v3
	s_waitcnt lgkmcnt(1)
	v_cvt_pk_bf16_f32 v2, v12, v13
	s_waitcnt lgkmcnt(0)
	v_cvt_pk_bf16_f32 v3, v14, v15
	global_store_dwordx4 v[16:17], v[0:3], off
	s_barrier

; #define LAS __attribute__((address_space(3)))
; #define GASP __attribute__((address_space(1)))
; __device__ __forceinline__ void transpose_item(const float* W, int K, int N, bf16_t* WT, int item, int gu, LAS float* tile,
;                                                const float* gam = nullptr, const float* bet = nullptr, float* c1p = nullptr, float* c2p = nullptr) {
;     const int tid = threadIdx.x, nblk = N / 64, kb = item / nblk, nb = item % nblk, k0 = kb * 64, n0 = nb * 64;
;     { const int r = tid >> 3, c8 = (tid & 7) * 8; const float* src = W + (size_t)(k0 + r) * N + n0 + c8;
;       const f32x4 a = *(const GASP f32x4*)src, b = *(const GASP f32x4*)(src + 4);
;       LAS float* t = tile + r * 65 + c8; t[0] = a[0]; t[1] = a[1]; t[2] = a[2]; t[3] = a[3]; t[4] = b[0]; t[5] = b[1]; t[6] = b[2]; t[7] = b[3]; }
;     __syncthreads();
;     { const int n = tid >> 3, k8 = (tid & 7) * 8; const LAS float* t = tile + k8 * 65 + n;
;       float w[8];
; #pragma unroll
;       for (int i = 0; i < 8; ++i) w[i] = t[i * 65];
;       int nn = n0 + n; if (gu) nn = (nn < FF) ? ((nn >> 7) * 256 + (nn & 127)) : (((nn - FF) >> 7) * 256 + 128 + ((nn - FF) & 127));
;       float s2 = 0.f;
;       if (gam) {
; #pragma unroll
;           for (int i = 0; i < 8; ++i) { s2 += bet[k0 + k8 + i] * w[i]; w[i] *= gam[k0 + k8 + i]; }
; __device__ __forceinline__ void phase_prep(const Params& p, LAS unsigned char* lds) {
;     ...
;         if (r < I_IN) { transpose_item(p.in[11], D, INC, (bf16_t*)(ws + O_WIN), r, 0, tile, p.in[9], p.in[10], (float*)(ws + O_C1P) + C_IN, (float*)(ws + O_C2P) + C_IN); continue; } r -= I_IN;
.LBB0_52:
	s_andn2_b64 vcc, exec, s[8:9]
	s_cbranch_vccnz .LBB0_61
	s_add_i32 s8, s90, 0xef80
	s_and_b32 s9, s8, 0xffff
	s_mul_i32 s9, s9, 0xcccd
	s_lshr_b32 s91, s9, 21
	s_lshl_b32 s10, s91, 6
	s_mul_i32 s9, s91, 40
	v_add_u32_e32 v0, s10, v5
	s_sub_i32 s11, s8, s9
	v_mul_u32_u24_e32 v0, 0xa00, v0
	v_lshlrev_b32_e32 v6, 2, v0
	s_lshl_b32 s8, s11, 8
	v_lshl_add_u64 v[0:1], s[26:27], 0, v[6:7]
	s_and_b32 s96, s8, 0x3ff00
	v_lshl_add_u64 v[0:1], v[0:1], 0, s[96:97]
	v_mov_b32_e32 v9, v7
	v_lshl_add_u64 v[12:13], v[0:1], 0, v[8:9]
	global_load_dwordx4 v[0:3], v[12:13], off nt
	s_nop 0
	global_load_dwordx4 v[12:15], v[12:13], off offset:16 nt
	v_cndmask_b32_e64 v6, 0, 1, s[92:93]
	v_cmp_ne_u32_e64 s[8:9], 1, v6
	s_andn2_b64 vcc, exec, s[92:93]
	s_cbranch_vccnz .Lgm_b
	v_or_b32_e32 v40, s10, v4
	v_lshlrev_b32_e32 v40, 2, v40
	global_load_dwordx4 v[24:27], v40, s[24:25]
	global_load_dwordx4 v[28:31], v40, s[24:25] offset:16
	global_load_dwordx4 v[32:35], v40, s[22:23]
	global_load_dwordx4 v[36:39], v40, s[22:23] offset:16

; #define LAS __attribute__((address_space(3)))
; #define GASP __attribute__((address_space(1)))
; __device__ __forceinline__ void transpose_item(const float* W, int K, int N, bf16_t* WT, int item, int gu, LAS float* tile,
;                                                const float* gam = nullptr, const float* bet = nullptr, float* c1p = nullptr, float* c2p = nullptr) {
;     const int tid = threadIdx.x, nblk = N / 64, kb = item / nblk, nb = item % nblk, k0 = kb * 64, n0 = nb * 64;
;     { const int r = tid >> 3, c8 = (tid & 7) * 8; const float* src = W + (size_t)(k0 + r) * N + n0 + c8;
;       const f32x4 a = *(const GASP f32x4*)src, b = *(const GASP f32x4*)(src + 4);
;       LAS float* t = tile + r * 65 + c8; t[0] = a[0]; t[1] = a[1]; t[2] = a[2]; t[3] = a[3]; t[4] = b[0]; t[5] = b[1]; t[6] = b[2]; t[7] = b[3]; }
;     __syncthreads();
;     { const int n = tid >> 3, k8 = (tid & 7) * 8; const LAS float* t = tile + k8 * 65 + n;
;       float w[8];
; #pragma unroll
;       for (int i = 0; i < 8; ++i) w[i] = t[i * 65];
;       int nn = n0 + n; if (gu) nn = (nn < FF) ? ((nn >> 7) * 256 + (nn & 127)) : (((nn - FF) >> 7) * 256 + 128 + ((nn - FF) & 127));
;       float s2 = 0.f;
;       if (gam) {
; #pragma unroll
;           for (int i = 0; i < 8; ++i) { s2 += bet[k0 + k8 + i] * w[i]; w[i] *= gam[k0 + k8 + i]; }
;       }
;       u32x4 o; o.x = pk2(w[0], w[1]); o.y = pk2(w[2], w[3]); o.z = pk2(w[4], w[5]); o.w = pk2(w[6], w[7]);
;       *(GASP u32x4*)(WT + (size_t)nn * K + k0 + k8) = o;
;       if (gam) {
;           float s1 = ((__uint_as_float(o.x << 16) + __uint_as_float(o.x & 0xffff0000u)) + (__uint_as_float(o.y << 16) + __uint_as_float(o.y & 0xffff0000u)))
;                    + ((__uint_as_float(o.z << 16) + __uint_as_float(o.z & 0xffff0000u)) + (__uint_as_float(o.w << 16) + __uint_as_float(o.w & 0xffff0000u)));
;           s1 += __shfl_xor(s1, 1); s1 += __shfl_xor(s1, 2); s1 += __shfl_xor(s1, 4);
;           s2 += __shfl_xor(s2, 1); s2 += __shfl_xor(s2, 2); s2 += __shfl_xor(s2, 4);
;           if ((tid & 7) == 0) { c1p[(size_t)kb * NC12 + nn] = s1; c2p[(size_t)kb * NC12 + nn] = s2; }
;       } }
;     __syncthreads();
; }
; __device__ __forceinline__ void phase_prep(const Params& p, LAS unsigned char* lds) {
;     ...
;         if (r < I_DN) { transpose_item(p.in[31], FF, D, (bf16_t*)(ws + O_WDN2), r, 0, tile); continue; } r -= I_DN;
.LBB0_62:
	s_andn2_b64 vcc, exec, s[8:9]
	s_cbranch_vccnz .LBB0_64
	s_add_i32 s8, s5, 0x3c900
	s_and_b32 s10, s8, 0x3ffc0
	v_readlane_b32 s8, v252, 1
	v_readlane_b32 s9, v252, 2
	s_load_dwordx2 s[8:9], s[8:9], 0xf8
	s_and_b32 s11, s0, 0x3c0
	v_add_lshl_u32 v6, s10, v5, 12
	s_lshl_b32 s96, s11, 2
	v_mov_b32_e32 v9, v7
	s_waitcnt lgkmcnt(0)
	v_lshl_add_u64 v[0:1], s[8:9], 0, v[6:7]
	v_lshl_add_u64 v[0:1], v[0:1], 0, s[96:97]
	v_lshl_add_u64 v[12:13], v[0:1], 0, v[8:9]
	global_load_dwordx4 v[0:3], v[12:13], off nt
	s_nop 0
	global_load_dwordx4 v[12:15], v[12:13], off offset:16 nt
	v_add_u32_e32 v6, s11, v5
	v_mul_u32_u24_e32 v6, 0xb00, v6
	v_lshlrev_b32_e32 v6, 1, v6
	v_lshl_add_u64 v[16:17], s[78:79], 0, v[6:7]
	s_lshl_b32 s96, s10, 1
	v_mov_b32_e32 v11, v7
	v_lshl_add_u64 v[16:17], v[16:17], 0, s[96:97]
	v_lshl_add_u64 v[16:17], v[16:17], 0, v[10:11]
	s_waitcnt vmcnt(0)
	ds_write2_b32 v18, v0, v1 offset1:1
	ds_write2_b32 v18, v2, v3 offset0:2 offset1:3
	ds_write2_b32 v18, v12, v13 offset0:4 offset1:5
	ds_write2_b32 v18, v14, v15 offset0:6 offset1:7
	s_waitcnt lgkmcnt(0)
	s_barrier
	ds_read2_b32 v[0:1], v19 offset1:65
	ds_read2_b32 v[2:3], v19 offset0:130 offset1:195
	ds_read2_b32 v[12:13], v22 offset0:4 offset1:69
	ds_read2_b32 v[14:15], v22 offset0:134 offset1:199
	s_waitcnt lgkmcnt(3)
	v_cvt_pk_bf16_f32 v0, v0, v1
	s_waitcnt lgkmcnt(2)
	v_cvt_pk_bf16_f32 v1, v2, v3
	s_waitcnt lgkmcnt(1)
	v_cvt_pk_bf16_f32 v2, v12, v13
	s_waitcnt lgkmcnt(0)
	v_cvt_pk_bf16_f32 v3, v14, v15
	global_store_dwordx4 v[16:17], v[0:3], off
	s_barrier

; #define LAS __attribute__((address_space(3)))
; #define GASP __attribute__((address_space(1)))
; __device__ __forceinline__ void transpose_item(const float* W, int K, int N, bf16_t* WT, int item, int gu, LAS float* tile,
;                                                const float* gam = nullptr, const float* bet = nullptr, float* c1p = nullptr, float* c2p = nullptr) {
;     const int tid = threadIdx.x, nblk = N / 64, kb = item / nblk, nb = item % nblk, k0 = kb * 64, n0 = nb * 64;
;     { const int r = tid >> 3, c8 = (tid & 7) * 8; const float* src = W + (size_t)(k0 + r) * N + n0 + c8;
;       const f32x4 a = *(const GASP f32x4*)src, b = *(const GASP f32x4*)(src + 4);
;       LAS float* t = tile + r * 65 + c8; t[0] = a[0]; t[1] = a[1]; t[2] = a[2]; t[3] = a[3]; t[4] = b[0]; t[5] = b[1]; t[6] = b[2]; t[7] = b[3]; }
;     __syncthreads();
;     { const int n = tid >> 3, k8 = (tid & 7) * 8; const LAS float* t = tile + k8 * 65 + n;
;       float w[8];
; #pragma unroll
;       for (int i = 0; i < 8; ++i) w[i] = t[i * 65];
;       int nn = n0 + n; if (gu) nn = (nn < FF) ? ((nn >> 7) * 256 + (nn & 127)) : (((nn - FF) >> 7) * 256 + 128 + ((nn - FF) & 127));
;       float s2 = 0.f;
;       if (gam) {
; #pragma unroll
;           for (int i = 0; i < 8; ++i) { s2 += bet[k0 + k8 + i] * w[i]; w[i] *= gam[k0 + k8 + i]; }
;       }
;       u32x4 o; o.x = pk2(w[0], w[1]); o.y = pk2(w[2], w[3]); o.z = pk2(w[4], w[5]); o.w = pk2(w[6], w[7]);
;       *(GASP u32x4*)(WT + (size_t)nn * K + k0 + k8) = o;
;       if (gam) {
;           float s1 = ((__uint_as_float(o.x << 16) + __uint_as_float(o.x & 0xffff0000u)) + (__uint_as_float(o.y << 16) + __uint_as_float(o.y & 0xffff0000u)))
;                    + ((__uint_as_float(o.z << 16) + __uint_as_float(o.z & 0xffff0000u)) + (__uint_as_float(o.w << 16) + __uint_as_float(o.w & 0xffff0000u)));
;           s1 += __shfl_xor(s1, 1); s1 += __shfl_xor(s1, 2); s1 += __shfl_xor(s1, 4);
;           s2 += __shfl_xor(s2, 1); s2 += __shfl_xor(s2, 2); s2 += __shfl_xor(s2, 4);
;           if ((tid & 7) == 0) { c1p[(size_t)kb * NC12 + nn] = s1; c2p[(size_t)kb * NC12 + nn] = s2; }
;       } }
;     __syncthreads();
; }
; __device__ __forceinline__ void phase_prep(const Params& p, LAS unsigned char* lds) {
;     ...
;         if (r < I_DN) { transpose_item(p.in[8], FF, D, (bf16_t*)(ws + O_WDN1), r, 0, tile); continue; } r -= I_DN;
.LBB0_65:
	s_andn2_b64 vcc, exec, s[8:9]
	s_cbranch_vccnz .LBB0_67
	s_add_i32 s8, s5, 0x3d400
	s_and_b32 s8, s8, 0x3ffc0
	s_and_b32 s9, s0, 0x3c0
	v_add_lshl_u32 v6, s8, v5, 12
	v_lshl_add_u64 v[0:1], s[20:21], 0, v[6:7]
	s_lshl_b32 s96, s9, 2
	v_lshl_add_u64 v[0:1], v[0:1], 0, s[96:97]
	v_mov_b32_e32 v9, v7
	v_lshl_add_u64 v[12:13], v[0:1], 0, v[8:9]
	global_load_dwordx4 v[0:3], v[12:13], off nt
	s_nop 0
	global_load_dwordx4 v[12:15], v[12:13], off offset:16 nt
	v_add_u32_e32 v6, s9, v5
	v_mul_u32_u24_e32 v6, 0xb00, v6
	v_lshlrev_b32_e32 v6, 1, v6
	v_lshl_add_u64 v[16:17], s[80:81], 0, v[6:7]
	s_lshl_b32 s96, s8, 1
	v_mov_b32_e32 v11, v7
	v_lshl_add_u64 v[16:17], v[16:17], 0, s[96:97]
	v_lshl_add_u64 v[16:17], v[16:17], 0, v[10:11]
	s_waitcnt vmcnt(0)
	ds_write2_b32 v18, v0, v1 offset1:1
	ds_write2_b32 v18, v2, v3 offset0:2 offset1:3
	ds_write2_b32 v18, v12, v13 offset0:4 offset1:5
	ds_write2_b32 v18, v14, v15 offset0:6 offset1:7
	s_waitcnt lgkmcnt(0)
	s_barrier
	ds_read2_b32 v[0:1], v19 offset1:65
	ds_read2_b32 v[2:3], v19 offset0:130 offset1:195
	ds_read2_b32 v[12:13], v22 offset0:4 offset1:69
	ds_read2_b32 v[14:15], v22 offset0:134 offset1:199
	s_waitcnt lgkmcnt(3)
	v_cvt_pk_bf16_f32 v0, v0, v1
	s_waitcnt lgkmcnt(2)
	v_cvt_pk_bf16_f32 v1, v2, v3
	s_waitcnt lgkmcnt(1)
	v_cvt_pk_bf16_f32 v2, v12, v13
	s_waitcnt lgkmcnt(0)
	v_cvt_pk_bf16_f32 v3, v14, v15
	global_store_dwordx4 v[16:17], v[0:3], off
	s_barrier

; #define LAS __attribute__((address_space(3)))
; #define GASP __attribute__((address_space(1)))
; __device__ __forceinline__ void transpose_item(const float* W, int K, int N, bf16_t* WT, int item, int gu, LAS float* tile,
;                                                const float* gam = nullptr, const float* bet = nullptr, float* c1p = nullptr, float* c2p = nullptr) {
;     const int tid = threadIdx.x, nblk = N / 64, kb = item / nblk, nb = item % nblk, k0 = kb * 64, n0 = nb * 64;
;     { const int r = tid >> 3, c8 = (tid & 7) * 8; const float* src = W + (size_t)(k0 + r) * N + n0 + c8;
;       const f32x4 a = *(const GASP f32x4*)src, b = *(const GASP f32x4*)(src + 4);
;       LAS float* t = tile + r * 65 + c8; t[0] = a[0]; t[1] = a[1]; t[2] = a[2]; t[3] = a[3]; t[4] = b[0]; t[5] = b[1]; t[6] = b[2]; t[7] = b[3]; }
;     __syncthreads();
;     { const int n = tid >> 3, k8 = (tid & 7) * 8; const LAS float* t = tile + k8 * 65 + n;
;       float w[8];
; #pragma unroll
;       for (int i = 0; i < 8; ++i) w[i] = t[i * 65];
;       int nn = n0 + n; if (gu) nn = (nn < FF) ? ((nn >> 7) * 256 + (nn & 127)) : (((nn - FF) >> 7) * 256 + 128 + ((nn - FF) & 127));
;       float s2 = 0.f;
;       if (gam) {
; #pragma unroll
;           for (int i = 0; i < 8; ++i) { s2 += bet[k0 + k8 + i] * w[i]; w[i] *= gam[k0 + k8 + i]; }
; __device__ __forceinline__ void phase_prep(const Params& p, LAS unsigned char* lds) {
;     ...
;         if (r < I_GU) { transpose_item(p.in[30], D, 2 * FF, (bf16_t*)(ws + O_WGU2), r, 1, tile, p.in[28], p.in[29], (float*)(ws + O_C1P) + C_GU2, (float*)(ws + O_C2P) + C_GU2); continue; } r -= I_GU;
.LBB0_68:
	s_andn2_b64 vcc, exec, s[8:9]
	s_cbranch_vccnz .LBB0_81
	s_add_i32 s8, s90, 0xfa80
	s_and_b32 s9, s8, 0xffff
	s_mul_i32 s9, s9, 0xba2f
	s_lshr_b32 s91, s9, 22
	s_lshr_b32 s9, s9, 16
	s_mul_i32 s10, s91, 0x58
	s_sub_i32 s8, s8, s10
	s_and_b32 s10, s9, 0xffc0
	v_add_u32_e32 v0, s10, v5
	s_lshl_b32 s8, s8, 6
	v_mul_u32_u24_e32 v0, 0x1600, v0
	s_and_b32 s8, s8, 0xffc0
	v_lshlrev_b32_e32 v6, 2, v0
	v_lshl_add_u64 v[0:1], s[30:31], 0, v[6:7]
	s_lshl_b32 s96, s8, 2
	v_lshl_add_u64 v[0:1], v[0:1], 0, s[96:97]
	v_mov_b32_e32 v9, v7
	v_lshl_add_u64 v[12:13], v[0:1], 0, v[8:9]
	global_load_dwordx4 v[0:3], v[12:13], off nt
	s_nop 0
	global_load_dwordx4 v[12:15], v[12:13], off offset:16 nt
	s_andn2_b64 vcc, exec, s[94:95]
	s_cbranch_vccnz .Lgm_c
	v_or_b32_e32 v40, s10, v4
	v_lshlrev_b32_e32 v40, 2, v40
	global_load_dwordx4 v[24:27], v40, s[28:29]
	global_load_dwordx4 v[28:31], v40, s[28:29] offset:16
	global_load_dwordx4 v[32:35], v40, s[50:51]
	global_load_dwordx4 v[36:39], v40, s[50:51] offset:16

; #define LAS __attribute__((address_space(3)))
; #define GASP __attribute__((address_space(1)))
; __device__ __forceinline__ void transpose_item(const float* W, int K, int N, bf16_t* WT, int item, int gu, LAS float* tile,
;                                                const float* gam = nullptr, const float* bet = nullptr, float* c1p = nullptr, float* c2p = nullptr) {
;     const int tid = threadIdx.x, nblk = N / 64, kb = item / nblk, nb = item % nblk, k0 = kb * 64, n0 = nb * 64;
;     { const int r = tid >> 3, c8 = (tid & 7) * 8; const float* src = W + (size_t)(k0 + r) * N + n0 + c8;
;       const f32x4 a = *(const GASP f32x4*)src, b = *(const GASP f32x4*)(src + 4);
;       LAS float* t = tile + r * 65 + c8; t[0] = a[0]; t[1] = a[1]; t[2] = a[2]; t[3] = a[3]; t[4] = b[0]; t[5] = b[1]; t[6] = b[2]; t[7] = b[3]; }
;     __syncthreads();
;     { const int n = tid >> 3, k8 = (tid & 7) * 8; const LAS float* t = tile + k8 * 65 + n;
;       float w[8];
; #pragma unroll
;       for (int i = 0; i < 8; ++i) w[i] = t[i * 65];
;       int nn = n0 + n; if (gu) nn = (nn < FF) ? ((nn >> 7) * 256 + (nn & 127)) : (((nn - FF) >> 7) * 256 + 128 + ((nn - FF) & 127));
; __device__ __forceinline__ void phase_prep(const Params& p, LAS unsigned char* lds) {
;     ...
;         if (r < I_GU) { transpose_item(p.in[7], D, 2 * FF, (bf16_t*)(ws + O_WGU1), r, 1, tile); continue; } r -= I_GU;
.LBB0_82:
	s_andn2_b64 vcc, exec, s[8:9]
	s_cbranch_vccnz .LBB0_22
	s_mul_hi_i32 s8, s90, 0x2e8ba2e9
	s_lshr_b32 s9, s8, 31
	s_ashr_i32 s8, s8, 4
	s_add_i32 s9, s8, s9
	s_lshl_b32 s8, s9, 6
	s_mul_i32 s10, s9, 0xffffea00
	s_add_i32 s10, s0, s10
	v_add_u32_e32 v2, s8, v5
	v_mov_b64_e32 v[0:1], s[18:19]
	s_movk_i32 s11, 0x5800
	v_mad_i64_i32 v[0:1], vcc, v2, s11, v[0:1]
	s_ashr_i32 s11, s10, 31
	v_lshl_add_u64 v[0:1], s[10:11], 2, v[0:1]
	v_mov_b32_e32 v9, v7
	v_lshl_add_u64 v[12:13], v[0:1], 0, v[8:9]
	global_load_dwordx4 v[0:3], v[12:13], off nt
	s_nop 0
	global_load_dwordx4 v[12:15], v[12:13], off offset:16 nt
	v_add_u32_e32 v9, s10, v5
	s_mulk_i32 s9, 0xd400
	v_cmp_lt_i32_e32 vcc, s56, v9
	v_add_u32_e32 v6, s9, v21
	v_and_b32_e32 v9, 0x7f, v9
	s_waitcnt vmcnt(0)
	ds_write2_b32 v18, v0, v1 offset1:1
	ds_write2_b32 v18, v2, v3 offset0:2 offset1:3
	ds_write2_b32 v18, v12, v13 offset0:4 offset1:5
	ds_write2_b32 v18, v14, v15 offset0:6 offset1:7
	s_waitcnt lgkmcnt(0)
	s_barrier
	ds_read2_b32 v[0:1], v19 offset1:65
	ds_read2_b32 v[2:3], v19 offset0:130 offset1:195
	ds_read2_b32 v[12:13], v22 offset0:4 offset1:69
	ds_read2_b32 v[14:15], v22 offset0:134 offset1:199
	s_and_saveexec_b64 s[10:11], vcc
	s_xor_b64 vcc, exec, s[10:11]
	v_add_u32_e32 v6, 0x7fffea00, v6
	v_and_b32_e32 v6, 0x7fffff00, v6
	v_or3_b32 v16, v9, v6, s57
	s_andn2_saveexec_b64 vcc, vcc
	s_cbranch_execz .LBB0_21
	s_movk_i32 s9, 0xff00
	v_and_or_b32 v16, v6, s9, v9
	s_branch .LBB0_21

; #define GASP __attribute__((address_space(1)))
; __device__ __forceinline__ void cvt_rows(const float* src, bf16_t* dst, size_t n8, size_t gtid, size_t gn) {
;     for (size_t i = gtid; i < n8; i += gn) { const f32x4 a = *(const GASP f32x4*)(src + 8 * i), b = *(const GASP f32x4*)(src + 8 * i + 4);
;         u32x4 o; o.x = pk2(a[0], a[1]); o.y = pk2(a[2], a[3]); o.z = pk2(b[0], b[1]); o.w = pk2(b[2], b[3]); *(GASP u32x4*)(dst + 8 * i) = o; }
; }
; __device__ __forceinline__ void phase_prep(const Params& p, LAS unsigned char* lds) {
;     ...
;     cvt_rows(p.in[0], (bf16_t*)(ws + O_XB), (size_t)NP * D / 8, gtid, gn);
.LBB0_89:
	global_load_dwordx4 v[10:13], v[4:5], off offset:-16 nt
	global_load_dwordx4 v[14:17], v[4:5], off nt
	v_lshl_add_u64 v[8:9], v[8:9], 0, s[18:19]
	v_cmp_lt_u64_e32 vcc, s[26:27], v[8:9]
	v_lshl_add_u64 v[4:5], v[4:5], 0, s[8:9]
	s_or_b64 s[24:25], vcc, s[24:25]
	s_waitcnt vmcnt(0)
	v_cvt_pk_bf16_f32 v10, v10, v11
	v_cvt_pk_bf16_f32 v11, v12, v13
	v_cvt_pk_bf16_f32 v12, v14, v15
	v_cvt_pk_bf16_f32 v13, v16, v17
	global_store_dwordx4 v[6:7], v[10:13], off
	v_lshl_add_u64 v[6:7], v[6:7], 0, s[22:23]
	s_andn2_b64 exec, exec, s[24:25]
	s_cbranch_execnz .LBB0_89

; #define GASP __attribute__((address_space(1)))
; __device__ __forceinline__ void cvt_rows(const float* src, bf16_t* dst, size_t n8, size_t gtid, size_t gn) {
;     for (size_t i = gtid; i < n8; i += gn) { const f32x4 a = *(const GASP f32x4*)(src + 8 * i), b = *(const GASP f32x4*)(src + 8 * i + 4);
;         u32x4 o; o.x = pk2(a[0], a[1]); o.y = pk2(a[2], a[3]); o.z = pk2(b[0], b[1]); o.w = pk2(b[2], b[3]); *(GASP u32x4*)(dst + 8 * i) = o; }
; }
; __device__ __forceinline__ void phase_prep(const Params& p, LAS unsigned char* lds) {
;     ...
;     cvt_rows(p.in[1], (bf16_t*)(ws + O_XB) + (size_t)NP * D, (size_t)NS * D / 8, gtid, gn);
.LBB0_92:
	global_load_dwordx4 v[10:13], v[4:5], off offset:-16 nt
	global_load_dwordx4 v[14:17], v[4:5], off nt
	v_lshl_add_u64 v[8:9], v[8:9], 0, s[18:19]
	v_cmp_lt_u64_e32 vcc, s[24:25], v[8:9]
	v_lshl_add_u64 v[4:5], v[4:5], 0, s[10:11]
	s_or_b64 s[22:23], vcc, s[22:23]
	s_waitcnt vmcnt(0)
	v_cvt_pk_bf16_f32 v10, v10, v11
	v_cvt_pk_bf16_f32 v11, v12, v13
	v_cvt_pk_bf16_f32 v12, v14, v15
	v_cvt_pk_bf16_f32 v13, v16, v17
	global_store_dwordx4 v[6:7], v[10:13], off
	v_lshl_add_u64 v[6:7], v[6:7], 0, s[20:21]
	s_andn2_b64 exec, exec, s[22:23]
	s_cbranch_execnz .LBB0_92

; #define GASP __attribute__((address_space(1)))
; __device__ __forceinline__ void cvt_rows(const float* src, bf16_t* dst, size_t n8, size_t gtid, size_t gn) {
;     for (size_t i = gtid; i < n8; i += gn) { const f32x4 a = *(const GASP f32x4*)(src + 8 * i), b = *(const GASP f32x4*)(src + 8 * i + 4);
;         u32x4 o; o.x = pk2(a[0], a[1]); o.y = pk2(a[2], a[3]); o.z = pk2(b[0], b[1]); o.w = pk2(b[2], b[3]); *(GASP u32x4*)(dst + 8 * i) = o; }
; }
; __device__ __forceinline__ void phase_prep(const Params& p, LAS unsigned char* lds) {
;     ...
;     cvt_rows(p.in[6], (bf16_t*)(ws + O_MEMB), (size_t)4096 * D / 8, gtid, gn);
.LBB0_95:
	global_load_dwordx4 v[10:13], v[4:5], off offset:-16 nt
	global_load_dwordx4 v[14:17], v[4:5], off nt
	v_lshl_add_u64 v[8:9], v[8:9], 0, s[18:19]
	v_cmp_lt_u64_e32 vcc, s[22:23], v[8:9]
	v_lshl_add_u64 v[4:5], v[4:5], 0, s[10:11]
	s_or_b64 s[20:21], vcc, s[20:21]
	s_waitcnt vmcnt(0)
	v_cvt_pk_bf16_f32 v10, v10, v11
	v_cvt_pk_bf16_f32 v11, v12, v13
	v_cvt_pk_bf16_f32 v12, v14, v15
	v_cvt_pk_bf16_f32 v13, v16, v17
	global_store_dwordx4 v[6:7], v[10:13], off
	v_lshl_add_u64 v[6:7], v[6:7], 0, s[16:17]
	s_andn2_b64 exec, exec, s[20:21]
	s_cbranch_execnz .LBB0_95

; #define GASP __attribute__((address_space(1)))
; __device__ __forceinline__ void cvt_rows(const float* src, bf16_t* dst, size_t n8, size_t gtid, size_t gn) {
;     for (size_t i = gtid; i < n8; i += gn) { const f32x4 a = *(const GASP f32x4*)(src + 8 * i), b = *(const GASP f32x4*)(src + 8 * i + 4);
;         u32x4 o; o.x = pk2(a[0], a[1]); o.y = pk2(a[2], a[3]); o.z = pk2(b[0], b[1]); o.w = pk2(b[2], b[3]); *(GASP u32x4*)(dst + 8 * i) = o; }
; }
; __device__ __forceinline__ void phase_prep(const Params& p, LAS unsigned char* lds) {
;     ...
;     cvt_rows(p.in[4], (bf16_t*)(ws + O_MKB) + (size_t)4096 * D, (size_t)8192 * D / 8, gtid, gn);
;     cvt_rows(p.in[5], (bf16_t*)(ws + O_MVB) + (size_t)4096 * D, (size_t)8192 * D / 8, gtid, gn);
.LBB0_98:
	global_load_dwordx4 v[12:15], v[6:7], off offset:-16 nt
	global_load_dwordx4 v[16:19], v[6:7], off nt
	v_lshl_add_u64 v[10:11], v[10:11], 0, s[18:19]
	v_cmp_lt_u64_e32 vcc, s[20:21], v[10:11]
	v_lshl_add_u64 v[6:7], v[6:7], 0, s[10:11]
	s_or_b64 s[16:17], vcc, s[16:17]
	s_waitcnt vmcnt(0)
	v_cvt_pk_bf16_f32 v12, v12, v13
	v_cvt_pk_bf16_f32 v13, v14, v15
	v_cvt_pk_bf16_f32 v14, v16, v17
	v_cvt_pk_bf16_f32 v15, v18, v19
	global_store_dwordx4 v[8:9], v[12:15], off
	v_lshl_add_u64 v[8:9], v[8:9], 0, s[12:13]
	s_andn2_b64 exec, exec, s[16:17]
	s_cbranch_execnz .LBB0_98
	s_or_b64 exec, exec, s[16:17]
	s_mov_b64 s[0:1], 0x1d3a1000
	v_lshl_add_u64 v[2:3], s[14:15], 0, v[2:3]
	v_lshl_add_u64 v[4:5], v[4:5], 0, s[0:1]
	s_mov_b64 s[14:15], 0
	s_mov_b64 s[16:17], 0xfffff
	v_mov_b64_e32 v[6:7], v[0:1]
.LBB0_100:
	global_load_dwordx4 v[8:11], v[2:3], off offset:-16 nt
	global_load_dwordx4 v[12:15], v[2:3], off nt
	v_lshl_add_u64 v[6:7], v[6:7], 0, s[18:19]
	v_cmp_lt_u64_e32 vcc, s[16:17], v[6:7]
	v_lshl_add_u64 v[2:3], v[2:3], 0, s[10:11]
	s_or_b64 s[14:15], vcc, s[14:15]
	s_waitcnt vmcnt(1)
	v_cvt_pk_bf16_f32 v8, v8, v9
	v_cvt_pk_bf16_f32 v9, v10, v11
	s_waitcnt vmcnt(0)
	v_cvt_pk_bf16_f32 v10, v12, v13
	v_cvt_pk_bf16_f32 v11, v14, v15
	global_store_dwordx4 v[4:5], v[8:11], off
	v_lshl_add_u64 v[4:5], v[4:5], 0, s[12:13]
	s_andn2_b64 exec, exec, s[14:15]
	s_cbranch_execnz .LBB0_100
